# batched global loads in ret_out (5 staging + 2 q loads in one round trip, 4 gate loads together), batched memk item, swa_prompt staging hoist, on top of merged 4-phase GEMM loops
# speedup vs baseline: 1.0311x; 1.0166x over previous
.LBB0_539:
	s_cmpk_gt_i32 s6, 0x1ff
	s_mov_b64 s[0:1], -1
	v_writelane_b32 v244, s6, 58
	s_cbranch_scc0 .LBB0_567
	v_readlane_b32 s0, v244, 58
	s_cmpk_gt_u32 s0, 0x2ff
	s_mov_b64 s[0:1], -1
	s_cbranch_scc0 .LBB0_552
	v_readlane_b32 s0, v244, 58
	s_cmpk_gt_u32 s0, 0xaff
	s_mov_b64 s[0:1], -1
	s_cbranch_scc0 .LBB0_549
	v_readlane_b32 s0, v244, 58
	s_cmpk_gt_u32 s0, 0xeff
	s_mov_b64 s[0:1], -1
	s_cbranch_scc0 .LBB0_544
	v_readlane_b32 s0, v244, 58
	s_nop 1
	v_lshl_add_u32 v42, s0, 5, v41
	v_lshlrev_b64 v[0:1], 9, v[42:43]
	v_lshl_add_u64 v[14:15], v[64:65], 0, v[0:1]
	global_load_dwordx2 v[16:17], v[14:15], off
	global_load_dwordx2 v[18:19], v[14:15], off offset:512
	global_load_dwordx2 v[20:21], v[14:15], off offset:1024
	global_load_dwordx2 v[22:23], v[14:15], off offset:1536
	global_load_dwordx2 v[24:25], v[58:59], off
	global_load_dwordx2 v[26:27], v[60:61], off
	v_cmp_lt_i32_e32 vcc, v195, v194
	v_lshlrev_b64 v[6:7], 8, v[42:43]
	v_lshl_add_u64 v[6:7], v[62:63], 0, v[6:7]
	v_cndmask_b32_e32 v0, v193, v195, vcc
	v_cmp_lt_i32_e32 vcc, v196, v194
	v_lshlrev_b32_e32 v0, 2, v0
	s_nop 0
	v_cndmask_b32_e32 v1, v193, v196, vcc
	v_cmp_lt_i32_e32 vcc, v197, v194
	v_lshlrev_b32_e32 v1, 2, v1
	s_nop 0
	v_cndmask_b32_e32 v2, v193, v197, vcc
	v_cmp_lt_i32_e32 vcc, v198, v194
	v_lshlrev_b32_e32 v2, 2, v2
	s_nop 0
	v_cndmask_b32_e32 v3, v193, v198, vcc
	v_cmp_lt_i32_e32 vcc, v199, v194
	v_lshlrev_b32_e32 v3, 2, v3
	s_nop 0
	v_cndmask_b32_e32 v4, v193, v199, vcc
	v_cmp_lt_i32_e32 vcc, v200, v194
	v_lshlrev_b32_e32 v4, 2, v4
	s_nop 0
	v_cndmask_b32_e32 v5, v193, v200, vcc
	v_lshlrev_b32_e32 v5, 2, v5
	s_mov_b64 s[0:1], 0
	s_waitcnt vmcnt(2)
	v_pk_mul_f32 v[28:29], v[16:17], v[16:17]
	v_pk_mul_f32 v[30:31], v[18:19], v[18:19]
	v_pk_mul_f32 v[32:33], v[20:21], v[20:21]
	v_pk_mul_f32 v[34:35], v[22:23], v[22:23]
	v_add_f32_e32 v28, v28, v29
	v_add_f32_e32 v30, v30, v31
	v_add_f32_e32 v32, v32, v33
	v_add_f32_e32 v34, v34, v35
	ds_bpermute_b32 v29, v0, v28
	ds_bpermute_b32 v31, v0, v30
	ds_bpermute_b32 v33, v0, v32
	ds_bpermute_b32 v35, v0, v34
	s_waitcnt lgkmcnt(0)
	v_add_f32_e32 v28, v28, v29
	v_add_f32_e32 v30, v30, v31
	v_add_f32_e32 v32, v32, v33
	v_add_f32_e32 v34, v34, v35
	ds_bpermute_b32 v29, v1, v28
	ds_bpermute_b32 v31, v1, v30
	ds_bpermute_b32 v33, v1, v32
	ds_bpermute_b32 v35, v1, v34
	s_waitcnt lgkmcnt(0)
	v_add_f32_e32 v28, v28, v29
	v_add_f32_e32 v30, v30, v31
	v_add_f32_e32 v32, v32, v33
	v_add_f32_e32 v34, v34, v35
	ds_bpermute_b32 v29, v2, v28
	ds_bpermute_b32 v31, v2, v30
	ds_bpermute_b32 v33, v2, v32
	ds_bpermute_b32 v35, v2, v34
	s_waitcnt lgkmcnt(0)
	v_add_f32_e32 v28, v28, v29
	v_add_f32_e32 v30, v30, v31
	v_add_f32_e32 v32, v32, v33
	v_add_f32_e32 v34, v34, v35
	ds_bpermute_b32 v29, v3, v28
	ds_bpermute_b32 v31, v3, v30
	ds_bpermute_b32 v33, v3, v32
	ds_bpermute_b32 v35, v3, v34
	s_waitcnt lgkmcnt(0)
	v_add_f32_e32 v28, v28, v29
	v_add_f32_e32 v30, v30, v31
	v_add_f32_e32 v32, v32, v33
	v_add_f32_e32 v34, v34, v35
	ds_bpermute_b32 v29, v4, v28
	ds_bpermute_b32 v31, v4, v30
	ds_bpermute_b32 v33, v4, v32
	ds_bpermute_b32 v35, v4, v34
	s_waitcnt lgkmcnt(0)
	v_add_f32_e32 v28, v28, v29
	v_add_f32_e32 v30, v30, v31
	v_add_f32_e32 v32, v32, v33
	v_add_f32_e32 v34, v34, v35
	ds_bpermute_b32 v29, v5, v28
	ds_bpermute_b32 v31, v5, v30
	ds_bpermute_b32 v33, v5, v32
	ds_bpermute_b32 v35, v5, v34
	s_waitcnt lgkmcnt(0)
	v_add_f32_e32 v28, v28, v29
	v_add_f32_e32 v30, v30, v31
	v_add_f32_e32 v32, v32, v33
	v_add_f32_e32 v34, v34, v35
	v_fmamk_f32 v28, v28, 0x3c000000, v183
	v_fmamk_f32 v30, v30, 0x3c000000, v183
	v_fmamk_f32 v32, v32, 0x3c000000, v183
	v_fmamk_f32 v34, v34, 0x3c000000, v183
	v_rsq_f32_e32 v28, v28
	v_rsq_f32_e32 v30, v30
	v_rsq_f32_e32 v32, v32
	v_rsq_f32_e32 v34, v34
	s_nop 0
	v_pk_mul_f32 v[16:17], v[16:17], v[28:29] op_sel_hi:[1,0]
	v_pk_mul_f32 v[18:19], v[18:19], v[30:31] op_sel_hi:[1,0]
	v_pk_mul_f32 v[20:21], v[20:21], v[32:33] op_sel_hi:[1,0]
	v_pk_mul_f32 v[22:23], v[22:23], v[34:35] op_sel_hi:[1,0]
	s_waitcnt vmcnt(0)
	v_pk_mul_f32 v[16:17], v[24:25], v[16:17]
	v_pk_mul_f32 v[18:19], v[24:25], v[18:19]
	v_pk_mul_f32 v[20:21], v[24:25], v[20:21]
	v_pk_mul_f32 v[22:23], v[24:25], v[22:23]
	global_store_dwordx2 v[14:15], v[16:17], off nt
	global_store_dwordx2 v[14:15], v[18:19], off offset:512 nt
	global_store_dwordx2 v[14:15], v[20:21], off offset:1024 nt
	global_store_dwordx2 v[14:15], v[22:23], off offset:1536 nt
	v_pk_mul_f32 v[28:29], v[26:27], v[16:17]
	v_pk_mul_f32 v[30:31], v[26:27], v[18:19]
	v_pk_mul_f32 v[32:33], v[26:27], v[20:21]
	v_pk_mul_f32 v[34:35], v[26:27], v[22:23]
	v_cvt_pk_bf16_f32 v28, v28, v29
	v_cvt_pk_bf16_f32 v30, v30, v31
	v_cvt_pk_bf16_f32 v32, v32, v33
	v_cvt_pk_bf16_f32 v34, v34, v35
	global_store_dword v[6:7], v28, off
	global_store_dword v[6:7], v30, off offset:256
	global_store_dword v[6:7], v32, off offset:512
	global_store_dword v[6:7], v34, off offset:768
	v_or_b32_e32 v42, 3, v42

.LBB0_567:
	s_andn2_b64 vcc, exec, s[0:1]
	s_cbranch_vccnz .LBB0_538
	v_readlane_b32 s0, v244, 58
	s_and_b32 s24, s0, 1
	s_bfe_u32 s6, s0, 0x50001
	s_ashr_i32 s4, s0, 6
	s_cmp_eq_u32 s6, 0
	s_cselect_b64 s[0:1], -1, 0
	s_lshl_b32 s6, s6, 7
	s_ashr_i32 s5, s4, 31
	s_add_i32 s7, s6, 0xffffff80
	s_lshl_b64 s[4:5], s[4:5], 12
	s_ashr_i32 s13, s7, 31
	s_add_u32 s12, s4, s7
	s_addc_u32 s13, s5, s13
	s_lshl_b32 s16, s24, 7
	v_lshl_add_u64 v[8:9], v[72:73], 0, s[16:17]
	v_lshl_add_u64 v[10:11], v[74:75], 0, s[16:17]
	s_and_b64 vcc, exec, s[0:1]
	v_add_u32_e32 v0, v141, v143
	v_lshl_add_u64 v[32:33], s[12:13], 0, v[50:51]
	v_lshlrev_b64 v[32:33], 8, v[32:33]
	v_lshl_add_u64 v[34:35], v[8:9], 0, v[32:33]
	v_lshl_add_u64 v[32:33], v[10:11], 0, v[32:33]
	global_load_dwordx4 v[16:19], v[34:35], off
	global_load_dwordx4 v[20:23], v[32:33], off
	v_lshl_add_u64 v[32:33], s[12:13], 0, v[52:53]
	v_lshlrev_b64 v[32:33], 8, v[32:33]
	v_lshl_add_u64 v[34:35], v[8:9], 0, v[32:33]
	v_lshl_add_u64 v[32:33], v[10:11], 0, v[32:33]
	global_load_dwordx4 v[24:27], v[34:35], off
	global_load_dwordx4 v[28:31], v[32:33], off
	s_barrier
	s_cbranch_vccnz .LBB0_570
	v_mov_b32_e32 v3, s13
	v_or_b32_e32 v2, s12, v44
	v_lshlrev_b64 v[2:3], 8, v[2:3]
	v_lshl_add_u64 v[6:7], v[10:11], 0, v[2:3]
	v_lshl_add_u64 v[2:3], v[8:9], 0, v[2:3]
	global_load_dwordx4 v[2:5], v[2:3], off
	s_nop 0
	global_load_dwordx4 v[12:15], v[6:7], off
	s_mov_b64 s[14:15], -1
	s_waitcnt vmcnt(1)
	ds_write_b128 v0, v[2:5]
	s_waitcnt vmcnt(0)
	ds_write_b128 v0, v[12:15] offset:36864
	s_cbranch_execz .LBB0_571
	s_branch .LBB0_572

.LBB0_574:
	s_or_b64 exec, exec, s[18:19]
	v_add_u32_e32 v12, v141, v145
	s_waitcnt vmcnt(1)
	ds_write_b128 v12, v[4:7]
	s_waitcnt vmcnt(0)
	ds_write_b128 v12, v[0:3] offset:36864
	s_lshl_b32 s24, s24, 2
	s_and_b64 s[0:1], exec, s[0:1]
	v_cmp_lt_i32_e32 vcc, v199, v194
	s_cselect_b32 s14, 0x80, 0
	v_readlane_b32 s0, v245, 26
	v_readlane_b32 s1, v245, 27
	s_mov_b32 s7, s17
	v_readlane_b32 s36, v246, 22
	v_readlane_b32 s37, v246, 23
	v_readlane_b32 s38, v246, 24
	v_readlane_b32 s39, v246, 25
	v_readlane_b32 s40, v246, 26
	v_readlane_b32 s41, v246, 27
	v_readlane_b32 s36, v244, 26
	v_readlane_b32 s38, v244, 28
	v_readlane_b32 s40, v244, 30
	s_mov_b32 s25, 0
	s_mov_b64 s[18:19], -1
	v_readlane_b32 s44, v246, 30
	v_readlane_b32 s45, v246, 31
	v_readlane_b32 s37, v244, 27
	v_readlane_b32 s39, v244, 29
	v_readlane_b32 s41, v244, 31
	v_readlane_b32 s42, v246, 28
	v_readlane_b32 s43, v246, 29
	v_readlane_b32 s46, v246, 32
	v_readlane_b32 s47, v246, 33
	v_readlane_b32 s48, v246, 34
	v_readlane_b32 s49, v246, 35
	v_readlane_b32 s50, v246, 36
	v_readlane_b32 s51, v246, 37
	s_waitcnt vmcnt(0)
	ds_write_b128 v189, v[16:19]
	ds_write_b128 v189, v[20:23] offset:36864
	v_readlane_b32 s12, v244, 22
	v_readlane_b32 s13, v244, 23
	s_waitcnt vmcnt(0)
	ds_write_b128 v190, v[24:27]
	ds_write_b128 v190, v[28:31] offset:36864
	v_cndmask_b32_e32 v4, v193, v199, vcc
	v_cmp_lt_i32_e32 vcc, v200, v194
	v_lshlrev_b32_e32 v42, 2, v4
	v_mov_b32_e32 v1, s5
	v_cndmask_b32_e32 v4, v193, v200, vcc
	v_cmp_le_u32_e32 vcc, s14, v147
	s_and_b64 s[26:27], s[0:1], vcc
	v_readlane_b32 s0, v245, 28
	v_cmp_le_u32_e32 vcc, s14, v148
	v_readlane_b32 s1, v245, 29
	s_and_b64 s[28:29], s[0:1], vcc
	v_readlane_b32 s0, v245, 30
	v_cmp_le_u32_e32 vcc, s14, v149
	v_readlane_b32 s1, v245, 31
	s_and_b64 s[30:31], s[0:1], vcc
	v_readlane_b32 s0, v245, 32
	v_cmp_le_u32_e32 vcc, s14, v150
	v_readlane_b32 s1, v245, 33
	s_and_b64 s[8:9], s[0:1], vcc
	v_readlane_b32 s0, v245, 34
	v_cmp_le_u32_e32 vcc, s14, v151
	v_readlane_b32 s1, v245, 35
	s_and_b64 s[52:53], s[0:1], vcc
	v_readlane_b32 s0, v245, 36
	v_cmp_le_u32_e32 vcc, s14, v152
	v_readlane_b32 s1, v245, 37
	s_and_b64 s[54:55], s[0:1], vcc
	v_readlane_b32 s0, v245, 38
	v_cmp_le_u32_e32 vcc, s14, v153
	v_readlane_b32 s1, v245, 39
	s_and_b64 s[56:57], s[0:1], vcc
	v_readlane_b32 s0, v245, 40
	v_cmp_le_u32_e32 vcc, s14, v154
	v_readlane_b32 s1, v245, 41
	s_and_b64 s[58:59], s[0:1], vcc
	v_readlane_b32 s0, v245, 42
	v_cmp_le_u32_e32 vcc, s14, v155
	v_readlane_b32 s1, v245, 43
	s_and_b64 s[60:61], s[0:1], vcc
	v_readlane_b32 s0, v245, 44
	v_cmp_le_u32_e32 vcc, s14, v156
	v_readlane_b32 s1, v245, 45
	s_and_b64 s[62:63], s[0:1], vcc
	v_readlane_b32 s0, v245, 46
	v_cmp_le_u32_e32 vcc, s14, v157
	v_readlane_b32 s1, v245, 47
	s_and_b64 s[64:65], s[0:1], vcc
	v_readlane_b32 s0, v245, 48
	v_cmp_le_u32_e32 vcc, s14, v158
	v_readlane_b32 s1, v245, 49
	s_and_b64 s[66:67], s[0:1], vcc
	v_readlane_b32 s0, v245, 50
	v_cmp_le_u32_e32 vcc, s14, v159
	v_readlane_b32 s1, v245, 51
	s_and_b64 s[68:69], s[0:1], vcc
	v_readlane_b32 s0, v245, 52
	v_cmp_le_u32_e32 vcc, s14, v160
	v_readlane_b32 s1, v245, 53
	s_and_b64 s[70:71], s[0:1], vcc
	v_readlane_b32 s0, v245, 54
	v_cmp_le_u32_e32 vcc, s14, v161
	v_readlane_b32 s1, v245, 55
	s_and_b64 s[72:73], s[0:1], vcc
	v_readlane_b32 s0, v245, 56
	v_cmp_le_u32_e32 vcc, s14, v162
	v_readlane_b32 s1, v245, 57
	s_and_b64 s[74:75], s[0:1], vcc
	v_readlane_b32 s0, v245, 58
	v_cmp_le_u32_e32 vcc, s14, v163
	v_readlane_b32 s1, v245, 59
	s_and_b64 s[76:77], s[0:1], vcc
	v_readlane_b32 s0, v245, 60
	v_cmp_le_u32_e32 vcc, s14, v164
	v_readlane_b32 s1, v245, 61
	s_and_b64 s[78:79], s[0:1], vcc
	v_readlane_b32 s0, v245, 62
	v_cmp_le_u32_e32 vcc, s14, v165
	v_readlane_b32 s1, v245, 63
	s_and_b64 s[80:81], s[0:1], vcc
	v_readlane_b32 s0, v244, 0
	v_cmp_le_u32_e32 vcc, s14, v166
	v_readlane_b32 s1, v244, 1
	s_and_b64 s[82:83], s[0:1], vcc
	v_readlane_b32 s0, v244, 2
	v_cmp_le_u32_e32 vcc, s14, v167
	v_readlane_b32 s1, v244, 3
	s_and_b64 s[84:85], s[0:1], vcc
	v_readlane_b32 s0, v244, 4
	v_cmp_le_u32_e32 vcc, s14, v168
	v_readlane_b32 s1, v244, 5
	s_and_b64 s[86:87], s[0:1], vcc
	v_readlane_b32 s0, v244, 6
	v_cmp_le_u32_e32 vcc, s14, v169
	v_readlane_b32 s1, v244, 7
	s_and_b64 s[88:89], s[0:1], vcc
	v_readlane_b32 s0, v244, 8
	v_cmp_le_u32_e32 vcc, s14, v170
	v_readlane_b32 s1, v244, 9
	s_and_b64 s[90:91], s[0:1], vcc
	v_readlane_b32 s0, v244, 10
	v_cmp_le_u32_e32 vcc, s14, v171
	v_readlane_b32 s1, v244, 11
	s_and_b64 s[92:93], s[0:1], vcc
	v_readlane_b32 s0, v244, 12
	v_cmp_le_u32_e32 vcc, s14, v172
	v_readlane_b32 s1, v244, 13
	s_and_b64 s[94:95], s[0:1], vcc
	v_readlane_b32 s0, v244, 14
	v_cmp_le_u32_e32 vcc, s14, v173
	v_readlane_b32 s1, v244, 15
	s_and_b64 s[96:97], s[0:1], vcc
	v_readlane_b32 s0, v244, 16
	v_or_b32_e32 v0, s4, v54
	v_cmp_le_u32_e32 vcc, s14, v174
	v_readlane_b32 s1, v244, 17
	v_lshl_add_u64 v[2:3], v[0:1], 0, s[6:7]
	s_and_b64 s[6:7], s[0:1], vcc
	v_readlane_b32 s0, v244, 18
	v_cmp_le_u32_e32 vcc, s14, v175
	v_readlane_b32 s1, v244, 19
	v_readlane_b32 s4, v244, 20
	s_and_b64 s[0:1], s[0:1], vcc
	v_cmp_le_u32_e32 vcc, s14, v176
	v_readlane_b32 s5, v244, 21
	s_and_b64 s[4:5], s[4:5], vcc
	v_cmp_le_u32_e32 vcc, s14, v177
	s_and_b64 s[12:13], s[12:13], vcc
	v_cmp_le_u32_e32 vcc, s14, v178
	v_readlane_b32 s14, v244, 24
	v_lshlrev_b64 v[0:1], 10, v[2:3]
	v_lshlrev_b64 v[2:3], 11, v[2:3]
	v_readlane_b32 s15, v244, 25
	v_lshlrev_b32_e32 v83, 2, v4
	s_and_b64 s[14:15], s[14:15], vcc
	v_lshl_add_u64 v[86:87], v[76:77], 0, v[2:3]
	v_lshl_add_u64 v[88:89], v[80:81], 0, v[0:1]
	s_waitcnt lgkmcnt(0)
	s_barrier

.LBB0_722:
	s_or_b64 exec, exec, s[0:1]
	ds_read_b128 v[84:87], v81 offset:36864
	ds_read_b128 v[88:91], v81 offset:36928
	s_lshl_b32 s0, s88, 6
	v_lshlrev_b64 v[100:101], 9, v[40:41]
	s_lshl_b32 s2, s0, 1
	v_lshl_add_u64 v[150:151], v[100:101], 1, s[96:97]
	v_mov_b32_e32 v148, v38
	v_mov_b32_e32 v149, 0
	v_lshl_add_u64 v[150:151], v[150:151], 0, s[2:3]
	v_lshl_add_u64 v[150:151], v[150:151], 0, v[148:149]
	global_load_dwordx2 v[140:141], v[150:151], off nt
	global_load_dwordx2 v[142:143], v[150:151], off offset:32 nt
	global_load_dwordx2 v[144:145], v[150:151], off offset:64 nt
	global_load_dwordx2 v[146:147], v[150:151], off offset:96 nt
	s_mov_b64 s[0:1], 0x119a4400
	s_add_i32 s33, s33, s90
	v_lshl_add_u64 v[34:35], v[34:35], 0, s[86:87]
	s_waitcnt lgkmcnt(1)
	v_mfma_f32_16x16x32_bf16 v[84:87], v[84:87], v[4:7], 0
	ds_read_b128 v[92:95], v81 offset:39232
	ds_read_b128 v[96:99], v81 offset:41536
	s_waitcnt lgkmcnt(2)
	v_mfma_f32_16x16x32_bf16 v[84:87], v[88:91], v[0:3], v[84:87]
	ds_read_b128 v[88:91], v81 offset:39168
	s_waitcnt lgkmcnt(0)
	v_mfma_f32_16x16x32_bf16 v[88:91], v[88:91], v[4:7], 0
	v_mfma_f32_16x16x32_bf16 v[88:91], v[92:95], v[0:3], v[88:91]
	ds_read_b128 v[92:95], v81 offset:41472
	s_waitcnt lgkmcnt(0)
	v_mfma_f32_16x16x32_bf16 v[92:95], v[92:95], v[4:7], 0
	v_mfma_f32_16x16x32_bf16 v[92:95], v[96:99], v[0:3], v[92:95]
	ds_read_b128 v[96:99], v81 offset:43776
	s_waitcnt lgkmcnt(0)
	v_mfma_f32_16x16x32_bf16 v[4:7], v[96:99], v[4:7], 0
	ds_read_b128 v[96:99], v81 offset:43840
	s_waitcnt lgkmcnt(0)
	v_mfma_f32_16x16x32_bf16 v[2:5], v[96:99], v[0:3], v[4:7]
	v_mul_f32_e32 v0, v39, v75
	s_nop 3
	v_exp_f32_e32 v6, v0
	v_mov_b32_e32 v39, v25
	v_pk_fma_f32 v[22:23], v[6:7], v[86:87], v[22:23] op_sel_hi:[0,1,1]
	v_pk_fma_f32 v[20:21], v[6:7], v[84:85], v[20:21] op_sel_hi:[0,1,1]
	v_pk_mul_f32 v[0:1], v[22:23], v[22:23]
	v_pk_mul_f32 v[84:85], v[20:21], v[20:21]
	v_pk_fma_f32 v[14:15], v[6:7], v[90:91], v[14:15] op_sel_hi:[0,1,1]
	v_pk_mov_b32 v[86:87], v[84:85], v[0:1] op_sel:[1,0]
	v_mov_b32_e32 v85, v1
	v_pk_fma_f32 v[12:13], v[6:7], v[88:89], v[12:13] op_sel_hi:[0,1,1]
	v_pk_add_f32 v[84:85], v[86:87], v[84:85]
	v_pk_mul_f32 v[0:1], v[14:15], v[14:15]
	v_pk_mul_f32 v[86:87], v[12:13], v[12:13]
	v_pk_fma_f32 v[2:3], v[6:7], v[2:3], v[16:17] op_sel_hi:[0,1,1]
	v_pk_mov_b32 v[88:89], v[86:87], v[0:1] op_sel:[1,0]
	v_mov_b32_e32 v87, v1
	v_pk_add_f32 v[86:87], v[88:89], v[86:87]
	v_pk_fma_f32 v[10:11], v[6:7], v[94:95], v[10:11] op_sel_hi:[0,1,1]
	v_pk_fma_f32 v[8:9], v[6:7], v[92:93], v[8:9] op_sel_hi:[0,1,1]
	v_pk_fma_f32 v[0:1], v[6:7], v[4:5], v[18:19] op_sel_hi:[0,1,1]
	v_mul_f32_e32 v6, v2, v2
	v_pk_add_f32 v[4:5], v[84:85], v[84:85] op_sel:[0,1] op_sel_hi:[1,0]
	v_mul_f32_e32 v16, v3, v3
	v_mov_b32_e32 v5, v6
	v_pk_add_f32 v[6:7], v[86:87], v[86:87] op_sel:[0,1] op_sel_hi:[1,0]
	v_mul_f32_e32 v17, v0, v0
	v_mov_b32_e32 v7, v16
	v_pk_add_f32 v[4:5], v[4:5], v[6:7]
	v_mul_f32_e32 v6, v9, v9
	v_pk_fma_f32 v[6:7], v[8:9], v[8:9], v[6:7] op_sel_hi:[1,1,0]
	v_mul_f32_e32 v16, v11, v11
	v_mul_f32_e32 v18, v1, v1
	v_mov_b32_e32 v7, v17
	v_pk_fma_f32 v[16:17], v[10:11], v[10:11], v[16:17] op_sel_hi:[1,1,0]
	s_nop 0
	v_mov_b32_e32 v17, v18
	v_pk_add_f32 v[6:7], v[6:7], v[16:17]
	s_nop 0
	v_pk_add_f32 v[4:5], v[4:5], v[6:7]
	v_lshl_add_u64 v[6:7], v[100:101], 1, s[96:97]
	v_lshl_add_u64 v[6:7], v[6:7], 0, s[2:3]
	v_lshl_add_u64 v[16:17], v[6:7], 0, v[38:39]
	v_lshlrev_b64 v[6:7], 11, v[40:41]
	s_nop 0
	v_add_f32_e32 v4, v4, v5
	ds_bpermute_b32 v5, v76, v4
	v_lshl_add_u64 v[6:7], s[22:23], 0, v[6:7]
	v_lshl_add_u64 v[6:7], v[6:7], 0, s[2:3]
	v_lshl_add_u64 v[18:19], v[6:7], 0, v[38:39]
	v_lshl_add_u64 v[6:7], v[18:19], 0, s[0:1]
	s_waitcnt lgkmcnt(0)
	v_add_f32_e32 v4, v4, v5
	ds_bpermute_b32 v5, v77, v4
	s_mov_b32 s0, 0x119a4000
	v_add_co_u32_e64 v18, s[0:1], s0, v18
	s_waitcnt lgkmcnt(0)
	v_add_f32_e32 v4, v4, v5
	v_fmamk_f32 v4, v4, 0x3c800000, v82
	v_rsq_f32_e32 v4, v4
	v_addc_co_u32_e64 v19, s[0:1], 0, v19, s[0:1]
	v_readlane_b32 s0, v246, 1
	v_pk_mul_f32 v[20:21], v[20:21], v[4:5] op_sel_hi:[1,0]
	v_pk_mul_f32 v[22:23], v[22:23], v[4:5] op_sel_hi:[1,0]
	v_pk_mul_f32 v[12:13], v[12:13], v[4:5] op_sel_hi:[1,0]
	v_pk_mul_f32 v[14:15], v[14:15], v[4:5] op_sel_hi:[1,0]
	v_pk_mul_f32 v[8:9], v[8:9], v[4:5] op_sel_hi:[1,0]
	v_pk_mul_f32 v[10:11], v[10:11], v[4:5] op_sel_hi:[1,0]
	v_pk_mul_f32 v[2:3], v[2:3], v[4:5] op_sel_hi:[1,0]
	v_pk_mul_f32 v[0:1], v[0:1], v[4:5] op_sel_hi:[1,0]
	s_add_i32 s91, s91, s0
	s_cmpk_lt_i32 s91, 0x800
	v_readlane_b32 s1, v246, 2
	s_waitcnt vmcnt(0)
	v_mov_b32_e32 v40, v140
	v_mov_b32_e32 v41, v141
	v_lshlrev_b32_e32 v84, 16, v40
	v_and_b32_e32 v85, 0xffff0000, v40
	v_lshlrev_b32_e32 v40, 16, v41
	v_and_b32_e32 v41, 0xffff0000, v41
	v_pk_mul_f32 v[20:21], v[20:21], v[84:85]
	v_pk_mul_f32 v[22:23], v[22:23], v[40:41]
	v_cvt_pk_bf16_f32 v20, v20, v21
	v_cvt_pk_bf16_f32 v21, v22, v23
	global_store_dwordx2 v[18:19], v[20:21], off offset:1024
	s_nop 1
	v_mov_b32_e32 v18, v142
	v_mov_b32_e32 v19, v143
	v_lshlrev_b32_e32 v20, 16, v18
	v_and_b32_e32 v21, 0xffff0000, v18
	v_lshlrev_b32_e32 v18, 16, v19
	v_and_b32_e32 v19, 0xffff0000, v19
	v_pk_mul_f32 v[12:13], v[12:13], v[20:21]
	v_pk_mul_f32 v[14:15], v[14:15], v[18:19]
	v_cvt_pk_bf16_f32 v12, v12, v13
	v_cvt_pk_bf16_f32 v13, v14, v15
	global_store_dwordx2 v[6:7], v[12:13], off offset:32
	s_nop 1
	v_mov_b32_e32 v12, v144
	v_mov_b32_e32 v13, v145
	v_lshlrev_b32_e32 v14, 16, v12
	v_and_b32_e32 v15, 0xffff0000, v12
	v_lshlrev_b32_e32 v12, 16, v13
	v_and_b32_e32 v13, 0xffff0000, v13
	v_pk_mul_f32 v[8:9], v[8:9], v[14:15]
	v_pk_mul_f32 v[10:11], v[10:11], v[12:13]
	v_cvt_pk_bf16_f32 v8, v8, v9
	v_cvt_pk_bf16_f32 v9, v10, v11
	global_store_dwordx2 v[6:7], v[8:9], off offset:64
	s_nop 1
	v_mov_b32_e32 v8, v146
	v_mov_b32_e32 v9, v147
	v_lshlrev_b32_e32 v10, 16, v8
	v_and_b32_e32 v11, 0xffff0000, v8
	v_lshlrev_b32_e32 v4, 16, v9
	v_and_b32_e32 v5, 0xffff0000, v9
	v_pk_mul_f32 v[2:3], v[2:3], v[10:11]
	v_pk_mul_f32 v[0:1], v[0:1], v[4:5]
	v_cvt_pk_bf16_f32 v2, v2, v3
	v_cvt_pk_bf16_f32 v3, v0, v1
	global_store_dwordx2 v[6:7], v[2:3], off offset:96
	s_cbranch_scc0 .LBB0_743
.LBB0_723:
	s_bfe_u32 s88, s91, 0x30005
	v_cvt_f32_ubyte0_e32 v0, s88
	v_sub_f32_e32 v0, 0xc0a00000, v0
	s_mov_b32 s0, 0xc2fc0000
	v_cmp_gt_f32_e64 s[0:1], s0, v0
	s_ashr_i32 s92, s91, 8
	s_waitcnt vmcnt(0)
	v_cndmask_b32_e64 v1, 0, v27, s[0:1]
	v_add_f32_e32 v0, v0, v1
	v_exp_f32_e32 v0, v0
	s_and_b64 s[0:1], s[0:1], exec
	s_cselect_b32 s0, 0xffffffc0, 0
	s_ashr_i32 s93, s92, 31
	v_ldexp_f32 v0, v0, s0
	s_lshl_b64 s[0:1], s[92:93], 12
	s_and_b32 s89, s33, 0xf80
	s_or_b32 s92, s0, s89
	v_sub_f32_e32 v10, 1.0, v0
	s_lshl_b32 s2, s88, 7
	v_mov_b32_e32 v1, s1
	v_or_b32_e32 v0, s92, v26
	v_lshl_add_u64 v[4:5], v[30:31], 0, s[2:3]
	v_lshlrev_b64 v[8:9], 10, v[0:1]
	v_lshl_add_u64 v[0:1], v[4:5], 0, v[8:9]
	global_load_dwordx4 v[120:123], v[0:1], off nt
	v_lshl_add_u64 v[6:7], v[32:33], 0, s[2:3]
	s_mov_b32 s93, s1
	v_add_u32_e32 v24, s89, v42
	v_lshl_add_u64 v[40:41], s[0:1], 0, v[24:25]
	v_log_f32_e32 v39, v10
	v_lshl_add_u64 v[0:1], v[6:7], 0, v[8:9]
	global_load_dwordx4 v[124:127], v[0:1], off nt
	v_lshl_add_u64 v[0:1], s[92:93], 0, v[28:29]
	v_lshlrev_b64 v[8:9], 10, v[0:1]
	v_lshl_add_u64 v[0:1], v[4:5], 0, v[8:9]
	global_load_dwordx4 v[128:131], v[0:1], off nt
	v_lshl_add_u64 v[0:1], v[6:7], 0, v[8:9]
	global_load_dwordx4 v[132:135], v[0:1], off nt
	global_load_dwordx4 v[136:139], v[34:35], off nt
	v_lshlrev_b64 v[0:1], 10, v[40:41]
	v_lshl_add_u64 v[0:1], s[94:95], 0, v[0:1]
	v_lshl_add_u64 v[0:1], v[0:1], 0, s[2:3]
	v_lshl_add_u64 v[0:1], v[0:1], 0, v[36:37]
	global_load_dwordx4 v[4:7], v[0:1], off nt
	s_nop 0
	global_load_dwordx4 v[0:3], v[0:1], off offset:64 nt
	s_barrier
	s_waitcnt vmcnt(6)
	ds_write_b128 v78, v[120:123]
	s_waitcnt vmcnt(5)
	ds_write_b128 v78, v[124:127] offset:18432
	s_waitcnt vmcnt(4)
	ds_write_b128 v79, v[128:131]
	s_waitcnt vmcnt(3)
	ds_write_b128 v79, v[132:135] offset:18432
	s_waitcnt vmcnt(2)
	ds_write_b128 v80, v[136:139] offset:36864
	s_waitcnt lgkmcnt(0)
	s_barrier
	ds_read_b128 v[8:11], v81
	ds_read_b128 v[12:15], v81 offset:64
	s_waitcnt vmcnt(1) lgkmcnt(1)
	v_mfma_f32_16x16x32_bf16 v[8:11], v[8:11], v[4:7], 0
	s_waitcnt vmcnt(0) lgkmcnt(0)
	v_mfma_f32_16x16x32_bf16 v[8:11], v[12:15], v[0:3], v[8:11]
	v_mov_b32_e32 v12, 0
	v_mov_b32_e32 v13, 0
	v_mov_b32_e32 v14, 0
	v_mov_b32_e32 v15, 0
	s_and_saveexec_b64 s[0:1], s[10:11]
	s_cbranch_execz .LBB0_725
	ds_read_b128 v[12:15], v81 offset:2304
	ds_read_b128 v[16:19], v81 offset:2368
	s_waitcnt lgkmcnt(1)
	v_mfma_f32_16x16x32_bf16 v[12:15], v[12:15], v[4:7], 0
	s_waitcnt lgkmcnt(0)
	v_mfma_f32_16x16x32_bf16 v[12:15], v[16:19], v[0:3], v[12:15]
	v_mul_f32_e32 v16, v39, v47
	v_mul_f32_e32 v17, v39, v48
	v_mul_f32_e32 v18, v39, v49
	v_mul_f32_e32 v19, v39, v50
	v_exp_f32_e32 v16, v16
	v_exp_f32_e32 v17, v17
	v_exp_f32_e32 v18, v18
	v_exp_f32_e32 v19, v19
	v_pk_mul_f32 v[12:13], v[16:17], v[12:13]
	s_nop 0
	v_cndmask_b32_e64 v12, 0, v12, s[30:31]
	v_pk_mul_f32 v[14:15], v[18:19], v[14:15]
	v_cndmask_b32_e64 v13, 0, v13, s[28:29]
	v_cndmask_b32_e64 v14, 0, v14, s[26:27]
	v_cndmask_b32_e64 v15, 0, v15, s[24:25]

.LBB0_747:
	s_or_b64 exec, exec, s[0:1]
	ds_read_b128 v[84:87], v81 offset:36864
	ds_read_b128 v[88:91], v81 offset:36928
	s_lshl_b32 s0, s87, 6
	v_lshlrev_b64 v[100:101], 9, v[40:41]
	s_lshl_b32 s2, s0, 1
	v_lshl_add_u64 v[150:151], v[100:101], 1, s[96:97]
	v_mov_b32_e32 v148, v38
	v_mov_b32_e32 v149, 0
	v_lshl_add_u64 v[150:151], v[150:151], 0, s[2:3]
	v_lshl_add_u64 v[150:151], v[150:151], 0, v[148:149]
	global_load_dwordx2 v[140:141], v[150:151], off nt
	global_load_dwordx2 v[142:143], v[150:151], off offset:32 nt
	global_load_dwordx2 v[144:145], v[150:151], off offset:64 nt
	global_load_dwordx2 v[146:147], v[150:151], off offset:96 nt
	s_mov_b64 s[0:1], 0x119a4400
	s_addk_i32 s33, 0x7c00
	s_waitcnt lgkmcnt(1)
	v_mfma_f32_16x16x32_bf16 v[84:87], v[84:87], v[4:7], 0
	ds_read_b128 v[92:95], v81 offset:39232
	ds_read_b128 v[96:99], v81 offset:41536
	s_waitcnt lgkmcnt(2)
	v_mfma_f32_16x16x32_bf16 v[84:87], v[88:91], v[0:3], v[84:87]
	ds_read_b128 v[88:91], v81 offset:39168
	s_waitcnt lgkmcnt(0)
	v_mfma_f32_16x16x32_bf16 v[88:91], v[88:91], v[4:7], 0
	v_mfma_f32_16x16x32_bf16 v[88:91], v[92:95], v[0:3], v[88:91]
	ds_read_b128 v[92:95], v81 offset:41472
	s_waitcnt lgkmcnt(0)
	v_mfma_f32_16x16x32_bf16 v[92:95], v[92:95], v[4:7], 0
	v_mfma_f32_16x16x32_bf16 v[92:95], v[96:99], v[0:3], v[92:95]
	ds_read_b128 v[96:99], v81 offset:43776
	s_waitcnt lgkmcnt(0)
	v_mfma_f32_16x16x32_bf16 v[4:7], v[96:99], v[4:7], 0
	ds_read_b128 v[96:99], v81 offset:43840
	s_waitcnt lgkmcnt(0)
	v_mfma_f32_16x16x32_bf16 v[2:5], v[96:99], v[0:3], v[4:7]
	v_mul_f32_e32 v0, v39, v75
	s_nop 3
	v_exp_f32_e32 v6, v0
	v_mov_b32_e32 v39, v25
	v_pk_fma_f32 v[22:23], v[6:7], v[86:87], v[22:23] op_sel_hi:[0,1,1]
	v_pk_fma_f32 v[20:21], v[6:7], v[84:85], v[20:21] op_sel_hi:[0,1,1]
	v_pk_mul_f32 v[0:1], v[22:23], v[22:23]
	v_pk_mul_f32 v[84:85], v[20:21], v[20:21]
	v_pk_fma_f32 v[14:15], v[6:7], v[90:91], v[14:15] op_sel_hi:[0,1,1]
	v_pk_mov_b32 v[86:87], v[84:85], v[0:1] op_sel:[1,0]
	v_mov_b32_e32 v85, v1
	v_pk_fma_f32 v[12:13], v[6:7], v[88:89], v[12:13] op_sel_hi:[0,1,1]
	v_pk_add_f32 v[84:85], v[86:87], v[84:85]
	v_pk_mul_f32 v[0:1], v[14:15], v[14:15]
	v_pk_mul_f32 v[86:87], v[12:13], v[12:13]
	v_pk_fma_f32 v[2:3], v[6:7], v[2:3], v[16:17] op_sel_hi:[0,1,1]
	v_pk_mov_b32 v[88:89], v[86:87], v[0:1] op_sel:[1,0]
	v_mov_b32_e32 v87, v1
	v_pk_add_f32 v[86:87], v[88:89], v[86:87]
	v_pk_fma_f32 v[10:11], v[6:7], v[94:95], v[10:11] op_sel_hi:[0,1,1]
	v_pk_fma_f32 v[8:9], v[6:7], v[92:93], v[8:9] op_sel_hi:[0,1,1]
	v_pk_fma_f32 v[0:1], v[6:7], v[4:5], v[18:19] op_sel_hi:[0,1,1]
	v_mul_f32_e32 v6, v2, v2
	v_pk_add_f32 v[4:5], v[84:85], v[84:85] op_sel:[0,1] op_sel_hi:[1,0]
	v_mul_f32_e32 v16, v3, v3
	v_mov_b32_e32 v5, v6
	v_pk_add_f32 v[6:7], v[86:87], v[86:87] op_sel:[0,1] op_sel_hi:[1,0]
	v_mul_f32_e32 v17, v0, v0
	v_mov_b32_e32 v7, v16
	v_pk_add_f32 v[4:5], v[4:5], v[6:7]
	v_mul_f32_e32 v6, v9, v9
	v_pk_fma_f32 v[6:7], v[8:9], v[8:9], v[6:7] op_sel_hi:[1,1,0]
	v_mul_f32_e32 v16, v11, v11
	v_mul_f32_e32 v18, v1, v1
	v_mov_b32_e32 v7, v17
	v_pk_fma_f32 v[16:17], v[10:11], v[10:11], v[16:17] op_sel_hi:[1,1,0]
	s_nop 0
	v_mov_b32_e32 v17, v18
	v_pk_add_f32 v[6:7], v[6:7], v[16:17]
	s_nop 0
	v_pk_add_f32 v[4:5], v[4:5], v[6:7]
	v_lshl_add_u64 v[6:7], v[100:101], 1, s[96:97]
	v_lshl_add_u64 v[6:7], v[6:7], 0, s[2:3]
	v_lshl_add_u64 v[16:17], v[6:7], 0, v[38:39]
	v_lshlrev_b64 v[6:7], 11, v[40:41]
	s_nop 0
	v_add_f32_e32 v4, v4, v5
	ds_bpermute_b32 v5, v76, v4
	v_lshl_add_u64 v[6:7], s[22:23], 0, v[6:7]
	v_lshl_add_u64 v[6:7], v[6:7], 0, s[2:3]
	v_lshl_add_u64 v[18:19], v[6:7], 0, v[38:39]
	v_lshl_add_u64 v[6:7], v[18:19], 0, s[0:1]
	s_waitcnt lgkmcnt(0)
	v_add_f32_e32 v4, v4, v5
	ds_bpermute_b32 v5, v77, v4
	s_mov_b32 s0, 0x119a4000
	v_add_co_u32_e64 v18, s[0:1], s0, v18
	s_add_i32 s2, s86, 0xf8
	s_waitcnt lgkmcnt(0)
	v_add_f32_e32 v4, v4, v5
	v_fmamk_f32 v4, v4, 0x3c800000, v82
	v_rsq_f32_e32 v4, v4
	v_addc_co_u32_e64 v19, s[0:1], 0, v19, s[0:1]
	s_mov_b64 s[0:1], 0x1f0000
	v_pk_mul_f32 v[20:21], v[20:21], v[4:5] op_sel_hi:[1,0]
	v_pk_mul_f32 v[22:23], v[22:23], v[4:5] op_sel_hi:[1,0]
	v_pk_mul_f32 v[12:13], v[12:13], v[4:5] op_sel_hi:[1,0]
	v_pk_mul_f32 v[14:15], v[14:15], v[4:5] op_sel_hi:[1,0]
	v_pk_mul_f32 v[8:9], v[8:9], v[4:5] op_sel_hi:[1,0]
	v_pk_mul_f32 v[10:11], v[10:11], v[4:5] op_sel_hi:[1,0]
	v_pk_mul_f32 v[2:3], v[2:3], v[4:5] op_sel_hi:[1,0]
	v_pk_mul_f32 v[0:1], v[0:1], v[4:5] op_sel_hi:[1,0]
	v_lshl_add_u64 v[34:35], v[34:35], 0, s[0:1]
	s_cmpk_gt_i32 s86, 0x6ef
	s_mov_b32 s86, s2
	s_waitcnt vmcnt(0)
	v_mov_b32_e32 v40, v140
	v_mov_b32_e32 v41, v141
	v_lshlrev_b32_e32 v84, 16, v40
	v_and_b32_e32 v85, 0xffff0000, v40
	v_lshlrev_b32_e32 v40, 16, v41
	v_and_b32_e32 v41, 0xffff0000, v41
	v_pk_mul_f32 v[20:21], v[20:21], v[84:85]
	v_pk_mul_f32 v[22:23], v[22:23], v[40:41]
	v_cvt_pk_bf16_f32 v20, v20, v21
	v_cvt_pk_bf16_f32 v21, v22, v23
	global_store_dwordx2 v[18:19], v[20:21], off offset:1024
	s_nop 1
	v_mov_b32_e32 v18, v142
	v_mov_b32_e32 v19, v143
	v_lshlrev_b32_e32 v20, 16, v18
	v_and_b32_e32 v21, 0xffff0000, v18
	v_lshlrev_b32_e32 v18, 16, v19
	v_and_b32_e32 v19, 0xffff0000, v19
	v_pk_mul_f32 v[12:13], v[12:13], v[20:21]
	v_pk_mul_f32 v[14:15], v[14:15], v[18:19]
	v_cvt_pk_bf16_f32 v12, v12, v13
	v_cvt_pk_bf16_f32 v13, v14, v15
	global_store_dwordx2 v[6:7], v[12:13], off offset:32
	s_nop 1
	v_mov_b32_e32 v12, v144
	v_mov_b32_e32 v13, v145
	v_lshlrev_b32_e32 v14, 16, v12
	v_and_b32_e32 v15, 0xffff0000, v12
	v_lshlrev_b32_e32 v12, 16, v13
	v_and_b32_e32 v13, 0xffff0000, v13
	v_pk_mul_f32 v[8:9], v[8:9], v[14:15]
	v_pk_mul_f32 v[10:11], v[10:11], v[12:13]
	v_cvt_pk_bf16_f32 v8, v8, v9
	v_cvt_pk_bf16_f32 v9, v10, v11
	global_store_dwordx2 v[6:7], v[8:9], off offset:64
	s_nop 1
	v_mov_b32_e32 v8, v146
	v_mov_b32_e32 v9, v147
	v_lshlrev_b32_e32 v10, 16, v8
	v_and_b32_e32 v11, 0xffff0000, v8
	v_lshlrev_b32_e32 v4, 16, v9
	v_and_b32_e32 v5, 0xffff0000, v9
	v_pk_mul_f32 v[2:3], v[2:3], v[10:11]
	v_pk_mul_f32 v[0:1], v[0:1], v[4:5]
	v_cvt_pk_bf16_f32 v2, v2, v3
	v_cvt_pk_bf16_f32 v3, v0, v1
	global_store_dwordx2 v[6:7], v[2:3], off offset:96
	s_cbranch_scc1 .LBB0_768
.LBB0_748:
	s_bfe_u32 s87, s86, 0x30005
	v_cvt_f32_ubyte0_e32 v0, s87
	v_sub_f32_e32 v0, 0xc0a00000, v0
	s_mov_b32 s0, 0xc2fc0000
	v_cmp_gt_f32_e64 s[0:1], s0, v0
	s_ashr_i32 s88, s86, 8
	s_waitcnt vmcnt(0)
	v_cndmask_b32_e64 v1, 0, v27, s[0:1]
	v_add_f32_e32 v0, v0, v1
	v_exp_f32_e32 v0, v0
	s_and_b64 s[0:1], s[0:1], exec
	s_cselect_b32 s0, 0xffffffc0, 0
	s_ashr_i32 s89, s88, 31
	v_ldexp_f32 v0, v0, s0
	s_lshl_b64 s[0:1], s[88:89], 12
	s_and_b32 s90, s33, 0xf80
	s_or_b32 s88, s0, s90
	v_sub_f32_e32 v10, 1.0, v0
	s_lshl_b32 s2, s87, 7
	v_mov_b32_e32 v1, s1
	v_or_b32_e32 v0, s88, v26
	v_lshl_add_u64 v[4:5], v[30:31], 0, s[2:3]
	v_lshlrev_b64 v[8:9], 10, v[0:1]
	v_lshl_add_u64 v[0:1], v[4:5], 0, v[8:9]
	global_load_dwordx4 v[120:123], v[0:1], off nt
	v_lshl_add_u64 v[6:7], v[32:33], 0, s[2:3]
	s_mov_b32 s89, s1
	v_add_u32_e32 v24, s90, v42
	v_lshl_add_u64 v[40:41], s[0:1], 0, v[24:25]
	v_log_f32_e32 v39, v10
	v_lshl_add_u64 v[0:1], v[6:7], 0, v[8:9]
	global_load_dwordx4 v[124:127], v[0:1], off nt
	v_lshl_add_u64 v[0:1], s[88:89], 0, v[28:29]
	v_lshlrev_b64 v[8:9], 10, v[0:1]
	v_lshl_add_u64 v[0:1], v[4:5], 0, v[8:9]
	global_load_dwordx4 v[128:131], v[0:1], off nt
	v_lshl_add_u64 v[0:1], v[6:7], 0, v[8:9]
	global_load_dwordx4 v[132:135], v[0:1], off nt
	global_load_dwordx4 v[136:139], v[34:35], off nt
	v_lshlrev_b64 v[0:1], 10, v[40:41]
	v_lshl_add_u64 v[0:1], s[94:95], 0, v[0:1]
	v_lshl_add_u64 v[0:1], v[0:1], 0, s[2:3]
	v_lshl_add_u64 v[0:1], v[0:1], 0, v[36:37]
	global_load_dwordx4 v[4:7], v[0:1], off nt
	s_nop 0
	global_load_dwordx4 v[0:3], v[0:1], off offset:64 nt
	s_barrier
	s_waitcnt vmcnt(6)
	ds_write_b128 v78, v[120:123]
	s_waitcnt vmcnt(5)
	ds_write_b128 v78, v[124:127] offset:18432
	s_waitcnt vmcnt(4)
	ds_write_b128 v79, v[128:131]
	s_waitcnt vmcnt(3)
	ds_write_b128 v79, v[132:135] offset:18432
	s_waitcnt vmcnt(2)
	ds_write_b128 v80, v[136:139] offset:36864
	s_waitcnt lgkmcnt(0)
	s_barrier
	ds_read_b128 v[8:11], v81
	ds_read_b128 v[12:15], v81 offset:64
	s_waitcnt vmcnt(1) lgkmcnt(1)
	v_mfma_f32_16x16x32_bf16 v[8:11], v[8:11], v[4:7], 0
	s_waitcnt vmcnt(0) lgkmcnt(0)
	v_mfma_f32_16x16x32_bf16 v[8:11], v[12:15], v[0:3], v[8:11]
	v_mov_b32_e32 v12, 0
	v_mov_b32_e32 v13, 0
	v_mov_b32_e32 v14, 0
	v_mov_b32_e32 v15, 0
	s_and_saveexec_b64 s[0:1], s[10:11]
	s_cbranch_execz .LBB0_750
	ds_read_b128 v[12:15], v81 offset:2304
	ds_read_b128 v[16:19], v81 offset:2368
	s_waitcnt lgkmcnt(1)
	v_mfma_f32_16x16x32_bf16 v[12:15], v[12:15], v[4:7], 0
	s_waitcnt lgkmcnt(0)
	v_mfma_f32_16x16x32_bf16 v[12:15], v[16:19], v[0:3], v[12:15]
	v_mul_f32_e32 v16, v39, v47
	v_mul_f32_e32 v17, v39, v48
	v_mul_f32_e32 v18, v39, v49
	v_mul_f32_e32 v19, v39, v50
	v_exp_f32_e32 v16, v16
	v_exp_f32_e32 v17, v17
	v_exp_f32_e32 v18, v18
	v_exp_f32_e32 v19, v19
	v_pk_mul_f32 v[12:13], v[16:17], v[12:13]
	s_nop 0
	v_cndmask_b32_e64 v12, 0, v12, s[30:31]
	v_pk_mul_f32 v[14:15], v[18:19], v[14:15]
	v_cndmask_b32_e64 v13, 0, v13, s[28:29]
	v_cndmask_b32_e64 v14, 0, v14, s[26:27]
	v_cndmask_b32_e64 v15, 0, v15, s[24:25]
